# convert_item w_in transpose: 4 tile loads and 4 gain loads batched instead of 8 serialized global round trips (on top of prep staging batching)
# speedup vs baseline: 1.0137x; 1.0137x over previous
; DI uint32_t pack2(float a, float b) { f2_t v = {a, b}; bf2_t r = __builtin_convertvector(v, bf2_t); return __builtin_bit_cast(uint32_t, r); }
; DI int opaque_tid() { int t = threadIdx.x; asm volatile("" : "+v"(t)); return t; }
; template <bool MAP>
; DI void transpose_tile(const float* __restrict__ src, int N, int K, int Nvalid, const float* __restrict__ g,
;                        u16* __restrict__ dst, int ldd, int k0, int n0, float* sT) {
;   const int tid = opaque_tid();
;   const int cg = (tid & 15) * 4, kq = tid >> 4;
;   const int sc = MAP ? src_col(n0 + cg) : ((n0 + cg < Nvalid) ? n0 + cg : -1);
; #pragma unroll
;   for (int i = 0; i < 4; ++i) {
;     const int kk = i * 16 + kq;
;     float4 v = make_float4(0.f, 0.f, 0.f, 0.f);
;     if (sc >= 0) {
;       v = *(const float4*)(src + (size_t)(k0 + kk) * N + sc);
;       if (g) { const float gg = g[k0 + kk]; v.x *= gg; v.y *= gg; v.z *= gg; v.w *= gg; }
;     }
;     float* d = sT + kk * 65 + cg;
;     d[0] = v.x; d[1] = v.y; d[2] = v.z; d[3] = v.w;
;   }
;   __syncthreads();
;   const int n = tid >> 2, kc = (tid & 3) * 16;
;   uint32_t o[8];
; #pragma unroll
;   for (int j = 0; j < 8; ++j) o[j] = pack2(sT[(kc + 2 * j) * 65 + n], sT[(kc + 2 * j + 1) * 65 + n]);
;   uint4* d = (uint4*)(dst + (size_t)(n0 + n) * ldd + k0 + kc);
;   d[0] = make_uint4(o[0], o[1], o[2], o[3]);
;   d[1] = make_uint4(o[4], o[5], o[6], o[7]);
;   __syncthreads();
.LBB0_334:
	v_readlane_b32 s0, v254, 61
	v_readlane_b32 s1, v254, 62
	s_and_b32 s16, s58, 0x3c0
	v_ashrrev_i32_e32 v0, 4, v14
	v_cmp_lt_i32_e64 s[44:45], -1, v2
	v_lshl_add_u64 v[10:11], v[2:3], 2, s[0:1]
	v_mov_b32_e32 v96, 0
	v_mov_b32_e32 v97, 0
	v_mov_b32_e32 v98, 0
	v_mov_b32_e32 v99, 0
	v_mov_b32_e32 v100, 0
	v_mov_b32_e32 v101, 0
	v_mov_b32_e32 v102, 0
	v_mov_b32_e32 v103, 0
	v_mov_b32_e32 v104, 0
	v_mov_b32_e32 v105, 0
	v_mov_b32_e32 v106, 0
	v_mov_b32_e32 v107, 0
	v_mov_b32_e32 v108, 0
	v_mov_b32_e32 v109, 0
	v_mov_b32_e32 v110, 0
	v_mov_b32_e32 v111, 0
	v_mov_b32_e32 v116, 1.0
	v_mov_b32_e32 v117, 1.0
	v_mov_b32_e32 v118, 1.0
	v_mov_b32_e32 v119, 1.0
	v_lshlrev_b32_e32 v1, 2, v1
	s_movk_i32 s0, 0x104
	v_mul_lo_u32 v2, v0, s0
	v_add_u32_e32 v2, v1, v2
	s_and_saveexec_b64 s[0:1], s[44:45]
	s_cbranch_execz .Lcvin_skipA
	v_add_u32_e32 v12, s16, v0
	s_movk_i32 s5, 0x7520
	v_mad_i64_i32 v[120:121], s[12:13], v12, s5, v[10:11]
	global_load_dwordx4 v[96:99], v[120:121], off
	v_add_u32_e32 v13, 16, v12
	v_mad_i64_i32 v[120:121], s[12:13], v13, s5, v[10:11]
	global_load_dwordx4 v[100:103], v[120:121], off
	v_add_u32_e32 v13, 32, v12
	v_mad_i64_i32 v[120:121], s[12:13], v13, s5, v[10:11]
	global_load_dwordx4 v[104:107], v[120:121], off
	v_add_u32_e32 v13, 48, v12
	v_mad_i64_i32 v[120:121], s[12:13], v13, s5, v[10:11]
	global_load_dwordx4 v[108:111], v[120:121], off
	v_readlane_b32 s12, v254, 31
	v_readlane_b32 s13, v254, 32
	s_andn2_b64 vcc, exec, s[12:13]
	s_cbranch_vccnz .Lcvin_skipA
	v_readlane_b32 s12, v254, 63
	v_ashrrev_i32_e32 v13, 31, v12
	v_readlane_b32 s13, v255, 0
	s_nop 1
	v_lshl_add_u64 v[12:13], v[12:13], 2, s[12:13]
	global_load_dword v116, v[12:13], off
	global_load_dword v117, v[12:13], off offset:64
	global_load_dword v118, v[12:13], off offset:128
	global_load_dword v119, v[12:13], off offset:192
.Lcvin_skipA:
	s_or_b64 exec, exec, s[0:1]
	s_waitcnt vmcnt(0)
	v_mul_f32_e32 v96, v96, v116
	v_mul_f32_e32 v97, v97, v116
	v_mul_f32_e32 v98, v98, v116
	v_mul_f32_e32 v99, v99, v116
	v_mul_f32_e32 v100, v100, v117
	v_mul_f32_e32 v101, v101, v117
	v_mul_f32_e32 v102, v102, v117
	v_mul_f32_e32 v103, v103, v117
	v_mul_f32_e32 v104, v104, v118
	v_mul_f32_e32 v105, v105, v118
	v_mul_f32_e32 v106, v106, v118
	v_mul_f32_e32 v107, v107, v118
	v_mul_f32_e32 v108, v108, v119
	v_mul_f32_e32 v109, v109, v119
	v_mul_f32_e32 v110, v110, v119
	v_mul_f32_e32 v111, v111, v119
	ds_write2_b32 v2, v96, v97 offset1:1
	ds_write2_b32 v2, v98, v99 offset0:2 offset1:3
	v_add_u32_e32 v1, 0x1040, v2
	ds_write2_b32 v1, v100, v101 offset1:1
	v_add_u32_e32 v1, 0x1048, v2
	ds_write2_b32 v1, v102, v103 offset1:1
	v_add_u32_e32 v1, 0x2080, v2
	ds_write2_b32 v1, v104, v105 offset1:1
	v_add_u32_e32 v1, 0x2088, v2
	ds_write2_b32 v1, v106, v107 offset1:1
	v_add_u32_e32 v1, 0x30c0, v2
	ds_write2_b32 v1, v108, v109 offset1:1
	v_add_u32_e32 v1, 0x30c8, v2
	ds_write2_b32 v1, v110, v111 offset1:1
	v_lshlrev_b32_e32 v0, 4, v14
	v_and_b32_e32 v12, 48, v0
	v_and_b32_e32 v0, -4, v14
	v_mul_u32_u24_e32 v1, 0x41, v12
	v_lshl_add_u32 v10, v1, 2, v0
	s_waitcnt lgkmcnt(0)
	s_barrier
	ds_read2_b32 v[0:1], v10 offset1:65
	v_add_u32_e32 v7, 0x400, v10
	v_add_u32_e32 v9, 0x800, v10
	v_add_u32_e32 v11, 0xc00, v10
	v_readlane_b32 s0, v254, 57
	s_waitcnt lgkmcnt(0)
	v_cvt_pk_bf16_f32 v4, v0, v1
	ds_read2_b32 v[0:1], v10 offset0:130 offset1:195
	v_ashrrev_i32_e32 v2, 2, v14
	v_readlane_b32 s1, v254, 58
	v_add_u32_e32 v2, s14, v2
	s_lshl_b32 s16, s16, 1
	s_waitcnt lgkmcnt(0)
	v_cvt_pk_bf16_f32 v5, v0, v1
	ds_read2_b32 v[0:1], v7 offset0:4 offset1:69
	s_waitcnt lgkmcnt(0)
	v_cvt_pk_bf16_f32 v6, v0, v1
	ds_read2_b32 v[0:1], v7 offset0:134 offset1:199
	s_waitcnt lgkmcnt(0)
	v_cvt_pk_bf16_f32 v7, v0, v1
	ds_read2_b32 v[0:1], v9 offset0:8 offset1:73
	s_waitcnt lgkmcnt(0)
	v_cvt_pk_bf16_f32 v8, v0, v1
	ds_read2_b32 v[0:1], v9 offset0:138 offset1:203
	s_waitcnt lgkmcnt(0)
	v_cvt_pk_bf16_f32 v9, v0, v1
	ds_read2_b32 v[0:1], v11 offset0:12 offset1:77
	s_waitcnt lgkmcnt(0)
	v_cvt_pk_bf16_f32 v10, v0, v1
	ds_read2_b32 v[0:1], v11 offset0:142 offset1:207
	s_waitcnt lgkmcnt(0)
	v_cvt_pk_bf16_f32 v11, v0, v1
	v_mov_b64_e32 v[0:1], s[0:1]
	v_mad_i64_i32 v[0:1], s[0:1], v2, s24, v[0:1]
	v_lshl_add_u64 v[0:1], v[0:1], 0, s[16:17]
	v_lshlrev_b32_e32 v2, 1, v12
	v_lshl_add_u64 v[0:1], v[0:1], 0, v[2:3]
	global_store_dwordx4 v[0:1], v[4:7], off
	global_store_dwordx4 v[0:1], v[8:11], off offset:16
	s_barrier
